# grid-barrier poll loops: s_sleep removed from the back edge (waiters re-poll immediately)
# speedup vs baseline: 1.0007x; 1.0007x over previous
; __global__ void __launch_bounds__(256, 2) mega(Params p) {
;     ...
;   grid.sync();
.LBB0_133:
	global_load_dword v2, v0, s[2:3] offset:32 sc1
	s_waitcnt vmcnt(0)
	v_and_b32_e32 v2, 0xffff0000, v2
	v_cmp_ne_u32_e32 vcc, v2, v1
	s_or_b64 s[4:5], vcc, s[4:5]
	s_andn2_b64 exec, exec, s[4:5]
	s_cbranch_execnz .LBB0_133

; DI void gbar(unsigned char* ws, unsigned& epoch) {
;     ...
;     while (__hip_atomic_load(bar + 64 * (8 + g), __ATOMIC_RELAXED, __HIP_MEMORY_SCOPE_AGENT) < epoch) __builtin_amdgcn_s_sleep(1);
.LBB0_153:
	global_load_dword v0, v209, s[48:49] offset:2048 sc1
	s_waitcnt vmcnt(0)
	v_cmp_ge_u32_e32 vcc, v0, v243
	s_or_b64 s[8:9], vcc, s[8:9]
	s_andn2_b64 exec, exec, s[8:9]
	s_cbranch_execnz .LBB0_153

; DI void gbar(unsigned char* ws, unsigned& epoch) {
;     ...
;     while (__hip_atomic_load(bar + 64 * (8 + g), __ATOMIC_RELAXED, __HIP_MEMORY_SCOPE_AGENT) < epoch) __builtin_amdgcn_s_sleep(1);
.LBB0_604:
	global_load_dword v0, v209, s[48:49] offset:2048 sc1
	s_waitcnt vmcnt(0)
	v_cmp_ge_u32_e32 vcc, v0, v243
	s_or_b64 s[8:9], vcc, s[8:9]
	s_andn2_b64 exec, exec, s[8:9]
	s_cbranch_execnz .LBB0_604
	s_getpc_b64 s[98:99]
